# retention chunk loop: waits no longer drain the just-issued sample-state stream ops (slot B/D store-ack wait, K^T ladder +2, dh=1 STOREQK without waits when the slot ran, explicit wait in slot C)
# speedup vs baseline: 1.0233x; 1.0028x over previous
.LBB0_2451:
	s_cmp_ge_i32 s43, s26
	s_cbranch_scc1 .LBB0_2453
	s_ashr_i32 s38, s43, 6
	s_mul_i32 s38, s38, s96
	s_add_i32 s38, s38, s2
	s_ashr_i32 s39, s38, 31
	s_lshl_b64 s[38:39], s[38:39], 8
	s_waitcnt vmcnt(2)
	v_lshl_or_b32 v82, v128, 6, s38
	v_and_or_b32 v82, s43, 63, v82
	v_mov_b32_e32 v83, s39
	v_lshlrev_b64 v[82:83], 11, v[82:83]
	v_lshl_add_u64 v[82:83], s[68:69], 0, v[82:83]
	v_lshl_add_u64 v[82:83], v[126:127], 2, v[82:83]
	global_load_dwordx4 v[82:85], v[82:83], off nt
	s_add_i32 s43, s43, 1
	s_cmp_lg_u32 s5, 16
	s_cselect_b64 s[80:81], -1, 0
	s_cmp_eq_u32 s5, 16
	v_cndmask_b32_e64 v97, 0, v97, s[54:55]
	v_cndmask_b32_e64 v96, 0, v96, s[54:55]
	v_cndmask_b32_e64 v95, 0, v95, s[54:55]
	v_cndmask_b32_e64 v94, 0, v94, s[54:55]
	v_cndmask_b32_e64 v101, 0, v101, s[54:55]
	v_cndmask_b32_e64 v100, 0, v100, s[54:55]
	v_cndmask_b32_e64 v99, 0, v99, s[54:55]
	v_cndmask_b32_e64 v98, 0, v98, s[54:55]
	v_cndmask_b32_e64 v105, 0, v105, s[58:59]
	v_cndmask_b32_e64 v104, 0, v104, s[58:59]
	v_cndmask_b32_e64 v103, 0, v103, s[58:59]
	v_cndmask_b32_e64 v102, 0, v102, s[58:59]
	v_cndmask_b32_e64 v109, 0, v109, s[58:59]
	v_cndmask_b32_e64 v108, 0, v108, s[58:59]
	v_cndmask_b32_e64 v107, 0, v107, s[58:59]
	v_cndmask_b32_e64 v106, 0, v106, s[58:59]
	v_cndmask_b32_e64 v113, 0, v113, s[60:61]
	v_cndmask_b32_e64 v112, 0, v112, s[60:61]
	v_cndmask_b32_e64 v111, 0, v111, s[60:61]
	v_cndmask_b32_e64 v110, 0, v110, s[60:61]
	v_cndmask_b32_e64 v117, 0, v117, s[60:61]
	v_cndmask_b32_e64 v116, 0, v116, s[60:61]
	v_cndmask_b32_e64 v115, 0, v115, s[60:61]
	v_cndmask_b32_e64 v114, 0, v114, s[60:61]
	v_cndmask_b32_e64 v121, 0, v121, s[62:63]
	v_cndmask_b32_e64 v120, 0, v120, s[62:63]
	v_cndmask_b32_e64 v119, 0, v119, s[62:63]
	v_cndmask_b32_e64 v118, 0, v118, s[62:63]
	v_cndmask_b32_e64 v125, 0, v125, s[62:63]
	v_cndmask_b32_e64 v124, 0, v124, s[62:63]
	v_cndmask_b32_e64 v123, 0, v123, s[62:63]
	v_cndmask_b32_e64 v122, 0, v122, s[62:63]
	ds_write_b128 v241, v[98:101]
	ds_write_b128 v241, v[94:97] offset:34816
	ds_write_b128 v242, v[106:109]
	ds_write_b128 v242, v[102:105] offset:34816
	ds_write_b128 v243, v[114:117]
	ds_write_b128 v243, v[110:113] offset:34816
	ds_write_b128 v244, v[122:125]
	ds_write_b128 v244, v[118:121] offset:34816
	s_branch .Lqk_store_done
.Lslb_noproc:
	s_waitcnt vmcnt(0)
	s_branch .LBB0_2451

.Lqk_store_done:
	s_cbranch_scc1 .LBB0_2456
	v_cmp_gt_i32_e32 vcc, s23, v155
	s_or_b32 s38, s65, 16
	s_lshl_b32 s39, s65, 1
	v_cndmask_b32_e32 v86, 0, v155, vcc
	v_add_u32_e32 v86, s38, v86
	v_ashrrev_i32_e32 v87, 31, v86
	v_lshlrev_b64 v[90:91], 11, v[86:87]
	v_or_b32_e32 v90, v90, v154
	v_lshl_add_u64 v[86:87], s[12:13], 0, v[90:91]
	v_lshl_add_u64 v[90:91], s[18:19], 0, v[90:91]
	global_load_dwordx4 v[98:101], v[86:87], off
	s_add_u32 s54, s72, s39
	global_load_dwordx4 v[94:97], v[90:91], off
	s_addc_u32 s55, s73, 0
	v_cmp_gt_i32_e32 vcc, s23, v156
	s_nop 1
	v_cndmask_b32_e32 v86, 0, v156, vcc
	v_add_u32_e32 v86, s38, v86
	v_ashrrev_i32_e32 v87, 31, v86
	v_lshlrev_b64 v[90:91], 11, v[86:87]
	v_or_b32_e32 v90, v90, v154
	v_lshl_add_u64 v[86:87], s[12:13], 0, v[90:91]
	v_lshl_add_u64 v[90:91], s[18:19], 0, v[90:91]
	global_load_dwordx4 v[106:109], v[86:87], off
	global_load_dwordx4 v[102:105], v[90:91], off
	v_cmp_gt_i32_e32 vcc, s23, v240
	s_nop 1
	v_cndmask_b32_e32 v86, 0, v240, vcc
	v_add_u32_e32 v86, s38, v86
	v_ashrrev_i32_e32 v87, 31, v86
	v_lshlrev_b64 v[90:91], 11, v[86:87]
	v_or_b32_e32 v90, v90, v154
	v_lshl_add_u64 v[86:87], s[12:13], 0, v[90:91]
	v_lshl_add_u64 v[90:91], s[18:19], 0, v[90:91]
	global_load_dwordx4 v[114:117], v[86:87], off
	global_load_dwordx4 v[110:113], v[90:91], off
	v_cmp_gt_i32_e32 vcc, s23, v239
	s_nop 1
	v_cndmask_b32_e32 v86, 0, v239, vcc
	v_add_u32_e32 v86, s38, v86
	v_ashrrev_i32_e32 v87, 31, v86
	v_lshlrev_b64 v[90:91], 11, v[86:87]
	v_or_b32_e32 v90, v90, v154
	v_lshl_add_u64 v[86:87], s[12:13], 0, v[90:91]
	v_lshl_add_u64 v[90:91], s[18:19], 0, v[90:91]
	global_load_dwordx4 v[122:125], v[86:87], off
	global_load_dwordx4 v[118:121], v[90:91], off
	v_mov_b64_e32 v[90:91], s[54:55]
	v_mad_i64_i32 v[86:87], s[38:39], v155, s9, v[90:91]
	v_mov_b32_e32 v155, v81
	v_mad_i64_i32 v[90:91], s[38:39], v156, s9, v[90:91]
	v_lshl_add_u64 v[86:87], v[86:87], 0, v[154:155]
	v_lshl_add_u64 v[90:91], v[90:91], 0, v[154:155]
	global_load_dwordx4 v[86:89], v[86:87], off offset:32
	s_nop 0
	global_load_dwordx4 v[90:93], v[90:91], off offset:32
.LBB0_2456:
	s_cmp_gt_i32 s43, s26
	s_waitcnt lgkmcnt(0)
	s_barrier
	s_cbranch_scc1 .LBB0_2465
	v_mov_b32_e32 v126, v166
	s_cmp_lt_i32 s43, 1
	v_and_b32_e32 v128, 3, v126
	v_and_b32_e32 v126, -4, v126
	v_ashrrev_i32_e32 v127, 31, v126
	s_cbranch_scc1 .LBB0_2462
	s_add_i32 s38, s43, -1
	s_lshr_b32 s39, s38, 6
	s_and_b32 s59, s38, 63
	s_mul_i32 s38, s39, s96
	s_add_i32 s54, s38, s2
	s_lshl_b32 s38, s39, 12
	s_add_i32 s38, s38, 0
	v_lshl_or_b32 v129, v128, 6, s59
	s_add_i32 s38, s38, 0x1d800
	v_lshl_add_u32 v130, v129, 2, s38
	s_and_b32 s58, s54, 3
	ds_read2st64_b32 v[134:135], v130 offset1:4
	v_lshl_add_u32 v130, v126, 2, s38
	s_add_i32 s38, s58, 5
	v_cvt_f32_ubyte0_e32 v131, s38
	v_exp_f32_e64 v136, -v131
	ds_read_b128 v[130:133], v130 offset:2048
	s_ashr_i32 s55, s54, 31
	s_waitcnt lgkmcnt(1)
	v_mov_b32_e32 v138, v135
	s_lshl_b64 s[38:39], s[54:55], 19
	v_sub_f32_e32 v136, 1.0, v136
	s_waitcnt lgkmcnt(0)
	s_cmp_eq_u32 s5, 16
	s_cbranch_scc1 .Lslotc_w0
	s_waitcnt vmcnt(10)
	s_branch .Lslotc_wd

.Lslotc_wd:
	v_pk_mul_f32 v[132:133], v[132:133], v[138:139] op_sel_hi:[1,0]
	v_pk_mul_f32 v[130:131], v[130:131], v[138:139] op_sel_hi:[1,0]
	s_add_u32 s38, s14, s38
	v_pk_fma_f32 v[132:133], v[84:85], v[136:137], v[132:133] op_sel_hi:[1,0,1]
	v_pk_fma_f32 v[130:131], v[82:83], v[136:137], v[130:131] op_sel_hi:[1,0,1]
	s_addc_u32 s39, s6, s39
	v_lshlrev_b32_e32 v136, 11, v129
	v_mov_b32_e32 v137, v81
	v_lshl_add_u64 v[136:137], s[38:39], 0, v[136:137]
	v_lshl_add_u64 v[136:137], v[126:127], 2, v[136:137]
	v_pk_fma_f32 v[218:219], v[134:135], v[132:133], v[218:219] op_sel_hi:[0,1,1]
	s_cmp_lg_u32 s59, 63
	v_pk_fma_f32 v[220:221], v[134:135], v[130:131], v[220:221] op_sel_hi:[0,1,1]
	global_store_dwordx4 v[136:137], v[130:133], off nt
	s_cbranch_scc1 .LBB0_2462
	v_add_f32_dpp v129, v220, v220 quad_perm:[1,0,3,2] row_mask:0xf bank_mask:0xf bound_ctrl:1
	v_mov_b32_e32 v130, 0
	v_add_f32_dpp v131, v221, v221 quad_perm:[1,0,3,2] row_mask:0xf bank_mask:0xf bound_ctrl:1
	v_mov_b32_e32 v132, 0
	v_add_f32_dpp v133, v218, v218 quad_perm:[1,0,3,2] row_mask:0xf bank_mask:0xf bound_ctrl:1
	v_mov_b32_e32 v134, 0
	v_add_f32_dpp v135, v219, v219 quad_perm:[1,0,3,2] row_mask:0xf bank_mask:0xf bound_ctrl:1
	v_mov_b32_e32 v136, 0
	v_mov_b32_dpp v130, v129 quad_perm:[2,3,0,1] row_mask:0xf bank_mask:0xf
	v_mov_b32_dpp v132, v131 quad_perm:[2,3,0,1] row_mask:0xf bank_mask:0xf
	v_mov_b32_dpp v134, v133 quad_perm:[2,3,0,1] row_mask:0xf bank_mask:0xf
	v_mov_b32_dpp v136, v135 quad_perm:[2,3,0,1] row_mask:0xf bank_mask:0xf
	v_cmp_eq_u32_e32 vcc, 0, v128
	s_and_saveexec_b64 s[38:39], vcc
	s_cbranch_execz .LBB0_2461
	s_ashr_i32 s54, s54, 2
	s_ashr_i32 s55, s54, 31
	s_lshl_b64 s[54:55], s[54:55], 12
	s_add_u32 s54, s86, s54
	s_addc_u32 s55, s87, s55
	s_lshl_b32 s58, s58, 10
	s_add_u32 s54, s54, s58
	v_add_f32_e32 v133, v133, v134
	v_add_f32_e32 v131, v131, v132
	s_addc_u32 s55, s55, 0
	v_add_f32_e32 v135, v135, v136
	v_add_f32_e32 v129, v129, v130
	v_cvt_pk_bf16_f32 v130, v129, v131
	v_cvt_pk_bf16_f32 v131, v133, v135
	v_lshl_add_u64 v[132:133], v[126:127], 1, s[54:55]
	v_add_co_u32_e32 v132, vcc, 0x4080000, v132
	s_nop 1
	v_addc_co_u32_e32 v133, vcc, 0, v133, vcc
	global_store_dwordx2 v[132:133], v[130:131], off

.LBB0_2479:
	s_cmp_ge_i32 s43, s26
	s_cbranch_scc1 .LBB0_2481
	s_ashr_i32 s38, s43, 6
	s_mul_i32 s38, s38, s96
	s_add_i32 s38, s38, s2
	s_ashr_i32 s39, s38, 31
	s_lshl_b64 s[38:39], s[38:39], 8
	s_waitcnt vmcnt(2)
	v_lshl_or_b32 v82, v128, 6, s38
	v_and_or_b32 v82, s43, 63, v82
	v_mov_b32_e32 v83, s39
	v_lshlrev_b64 v[82:83], 11, v[82:83]
	v_lshl_add_u64 v[82:83], s[68:69], 0, v[82:83]
	v_lshl_add_u64 v[82:83], v[126:127], 2, v[82:83]
	global_load_dwordx4 v[82:85], v[82:83], off nt

.LBB0_2502:
	v_cvt_f32_ubyte0_e32 v32, s27
	v_mul_f32_e32 v32, v215, v32
	v_exp_f32_e32 v38, v32
	v_mov_b32_e32 v32, s91
	v_mad_u32_u24 v32, v217, s90, v32
	v_add_u32_e32 v32, v32, v222
	ds_read_b128 v[34:37], v32
	v_pk_mul_f32 v[14:15], v[14:15], v[38:39] op_sel_hi:[1,0]
	v_pk_mul_f32 v[12:13], v[12:13], v[38:39] op_sel_hi:[1,0]
	v_pk_mul_f32 v[10:11], v[10:11], v[38:39] op_sel_hi:[1,0]
	v_pk_mul_f32 v[8:9], v[8:9], v[38:39] op_sel_hi:[1,0]
	v_pk_mul_f32 v[6:7], v[6:7], v[38:39] op_sel_hi:[1,0]
	v_pk_mul_f32 v[4:5], v[4:5], v[38:39] op_sel_hi:[1,0]
	v_pk_mul_f32 v[2:3], v[2:3], v[38:39] op_sel_hi:[1,0]
	v_pk_mul_f32 v[0:1], v[0:1], v[38:39] op_sel_hi:[1,0]
	v_pk_mul_f32 v[30:31], v[30:31], v[38:39] op_sel_hi:[1,0]
	v_pk_mul_f32 v[28:29], v[28:29], v[38:39] op_sel_hi:[1,0]
	s_waitcnt vmcnt(9) lgkmcnt(0)
	v_mfma_f32_32x32x16_bf16 v[0:15], v[154:157], v[34:37], v[0:15]
	ds_read_b128 v[34:37], v32 offset:8704
	v_mul_f32_e64 v26, v26, v38
	v_mul_f32_e64 v27, v27, v38
	v_mul_f32_e64 v24, v24, v38
	v_mul_f32_e64 v25, v25, v38
	v_pk_mul_f32 v[22:23], v[22:23], v[38:39] op_sel_hi:[1,0]
	v_pk_mul_f32 v[20:21], v[20:21], v[38:39] op_sel_hi:[1,0]
	v_pk_mul_f32 v[18:19], v[18:19], v[38:39] op_sel_hi:[1,0]
	v_pk_mul_f32 v[16:17], v[16:17], v[38:39] op_sel_hi:[1,0]
	v_cndmask_b32_e64 v33, 0, 1, s[66:67]
	v_cmp_ne_u32_e64 s[54:55], 1, v33
	s_waitcnt lgkmcnt(0)
	v_mfma_f32_32x32x16_bf16 v[16:31], v[154:157], v[34:37], v[16:31]
	s_andn2_b64 vcc, exec, s[66:67]
	s_cbranch_vccnz .LBB0_2519
	ds_read_b128 v[34:37], v32 offset:32
	ds_read_b128 v[40:43], v32 offset:8736
	s_waitcnt vmcnt(8) lgkmcnt(1)
	v_mfma_f32_32x32x16_bf16 v[0:15], v[150:153], v[34:37], v[0:15]
	s_waitcnt lgkmcnt(0)
	v_mfma_f32_32x32x16_bf16 v[16:31], v[150:153], v[40:43], v[16:31]
	s_and_b64 vcc, exec, s[54:55]
	s_cbranch_vccz .LBB0_2520

.LBB0_2505:
	ds_read_b128 v[34:37], v32 offset:96
	ds_read_b128 v[40:43], v32 offset:8800
	s_waitcnt vmcnt(6) lgkmcnt(1)
	v_mfma_f32_32x32x16_bf16 v[0:15], v[142:145], v[34:37], v[0:15]
	s_waitcnt lgkmcnt(0)
	v_mfma_f32_32x32x16_bf16 v[16:31], v[142:145], v[40:43], v[16:31]
	s_and_b64 vcc, exec, s[54:55]
	s_cbranch_vccz .LBB0_2522

.LBB0_2507:
	ds_read_b128 v[34:37], v32 offset:160
	ds_read_b128 v[40:43], v32 offset:8864
	s_waitcnt vmcnt(4) lgkmcnt(1)
	v_mfma_f32_32x32x16_bf16 v[0:15], v[134:137], v[34:37], v[0:15]
	s_waitcnt lgkmcnt(0)
	v_mfma_f32_32x32x16_bf16 v[16:31], v[134:137], v[40:43], v[16:31]
	s_and_b64 vcc, exec, s[54:55]
	s_cbranch_vccz .LBB0_2524

.LBB0_2509:
	ds_read_b128 v[34:37], v32 offset:224
	ds_read_b128 v[40:43], v32 offset:8928
	s_waitcnt vmcnt(2) lgkmcnt(1)
	v_mfma_f32_32x32x16_bf16 v[0:15], v[126:129], v[34:37], v[0:15]
	s_waitcnt lgkmcnt(0)
	v_mfma_f32_32x32x16_bf16 v[16:31], v[126:129], v[40:43], v[16:31]

.LBB0_2520:
	ds_read_b128 v[34:37], v32 offset:64
	ds_read_b128 v[40:43], v32 offset:8768
	s_waitcnt vmcnt(7) lgkmcnt(1)
	v_mfma_f32_32x32x16_bf16 v[0:15], v[146:149], v[34:37], v[0:15]
	s_waitcnt lgkmcnt(0)
	v_mfma_f32_32x32x16_bf16 v[16:31], v[146:149], v[40:43], v[16:31]
	s_and_b64 vcc, exec, s[54:55]
	s_cbranch_vccz .LBB0_2505

.LBB0_2522:
	ds_read_b128 v[34:37], v32 offset:128
	ds_read_b128 v[40:43], v32 offset:8832
	s_waitcnt vmcnt(5) lgkmcnt(1)
	v_mfma_f32_32x32x16_bf16 v[0:15], v[138:141], v[34:37], v[0:15]
	s_waitcnt lgkmcnt(0)
	v_mfma_f32_32x32x16_bf16 v[16:31], v[138:141], v[40:43], v[16:31]
	s_and_b64 vcc, exec, s[54:55]
	s_cbranch_vccz .LBB0_2507

.LBB0_2524:
	ds_read_b128 v[34:37], v32 offset:192
	ds_read_b128 v[40:43], v32 offset:8896
	s_waitcnt vmcnt(3) lgkmcnt(1)
	v_mfma_f32_32x32x16_bf16 v[0:15], v[130:133], v[34:37], v[0:15]
	s_waitcnt lgkmcnt(0)
	v_mfma_f32_32x32x16_bf16 v[16:31], v[130:133], v[40:43], v[16:31]
	s_and_b64 vcc, exec, s[54:55]
	s_cbranch_vccz .LBB0_2509
	s_branch .LBB0_2510
